# attention softmax segment: canonicalising v_max triples, +0 row-sum seed and live-flag VGPR round trip removed
# speedup vs baseline: 1.0090x; 1.0090x over previous
; __device__ __forceinline__ bool softmax_pp(f32x16& p0, f32x16& p1, float& m_reg, float& l_reg, f32x16& negm, float& alpha, float& m_run, float dq, float nslope,
;                                            bf16x8& pa0, bf16x8& pa1, bf16x8& pa2, bf16x8& pa3) {
;     ...
;   float a = fmaxf(fmaxf(p0[0], p0[1]), p1[0]), bq = fmaxf(fmaxf(p0[2], p0[3]), p1[1]); a = fmaxf(fmaxf(a, p1[2]), p1[3]);
; #pragma unroll
;   for (int r = 4; r < 16; r += 4) { a = fmaxf(fmaxf(a, p0[r]), p0[r + 1]); bq = fmaxf(fmaxf(bq, p0[r + 2]), p0[r + 3]); a = fmaxf(fmaxf(a, p1[r]), p1[r + 1]); bq = fmaxf(fmaxf(bq, p1[r + 2]), p1[r + 3]); }
;   float pmax = fmaxf(a, bq);
;   { auto rr = __builtin_amdgcn_permlane32_swap(__float_as_uint(pmax), __float_as_uint(pmax), false, false);
;     pmax = fmaxf(__uint_as_float(rr[0]), __uint_as_float(rr[1])); }
;   alpha = 1.f;
;   { const float tmax = pmax + m_reg;
;     if (__all(tmax < m_run - TSKIP)) return false;
;     m_run = fmaxf(m_run, tmax); }
;   if (__builtin_expect(!__all(pmax <= THRL), 0)) { const float dl = fmaxf(pmax, 0.f); m_reg += dl; alpha = __builtin_amdgcn_exp2f(-dl);
; #pragma unroll
;     for (int r = 0; r < 16; ++r) { p0[r] -= dl; p1[r] -= dl; }
; #pragma unroll
;     for (int r = 0; r < 16; ++r) negm[r] = -m_reg; }
; #pragma unroll
;   for (int r = 0; r < 16; ++r) { p0[r] = __builtin_amdgcn_exp2f(p0[r]); p1[r] = __builtin_amdgcn_exp2f(p1[r]); }
;   float ps = 0;
; #pragma unroll
;   for (int r = 0; r < 16; ++r) ps += p0[r];
; #pragma unroll
;   for (int r = 0; r < 16; ++r) ps += p1[r];
;   { auto rr = __builtin_amdgcn_permlane32_swap(__float_as_uint(ps), __float_as_uint(ps), false, false);
;     ps = __uint_as_float(rr[0]) + __uint_as_float(rr[1]); }
;   l_reg = l_reg * alpha + ps;
;     ...
;   PK4(p0, 0, pa0); PK4(p0, 8, pa1); PK4(p1, 0, pa2); PK4(p1, 8, pa3);
.Lafter_bias_0:
	v_max_f32_e32 v0, v98, v99
	v_max3_f32 v14, v100, v101, v115
	v_max3_f32 v0, v0, v114, v116
	v_max3_f32 v0, v0, v117, v102
	v_max3_f32 v14, v14, v104, v105
	v_max3_f32 v0, v0, v103, v118
	v_max3_f32 v14, v14, v120, v121
	v_max3_f32 v0, v0, v119, v106
	v_max3_f32 v14, v14, v108, v109
	v_max3_f32 v0, v0, v107, v122
	v_max3_f32 v14, v14, v124, v125
	v_max3_f32 v0, v0, v123, v110
	v_max3_f32 v14, v14, v112, v113
	v_max3_f32 v0, v0, v111, v126
	v_max3_f32 v14, v14, v128, v129
	v_max3_f32 v0, v0, v127, v14
	v_mov_b32_e32 v14, v0
	s_nop 1
	v_permlane32_swap_b32_e32 v0, v14
	v_max_f32_e32 v167, v0, v14
	v_pk_add_f32 v[14:15], v[172:173], v[166:167]
	s_nop 0
	v_cmp_lt_f32_e32 vcc, v15, v14
	s_cmp_lg_u64 vcc, exec
	s_cselect_b64 s[14:15], -1, 0
	s_cmp_eq_u64 vcc, exec
	s_cbranch_scc1 .LBB0_370
	v_cmp_ge_f32_e32 vcc, s59, v167
	s_cmp_eq_u64 vcc, exec
	s_cbranch_scc0 .LBB0_395
	v_mov_b32_e32 v0, 1.0
.LBB0_369:
	v_max_f32_e32 v172, v172, v15
	v_exp_f32_e32 v2, v98
	v_exp_f32_e32 v3, v99
	v_exp_f32_e32 v4, v100
	v_exp_f32_e32 v5, v101
	v_exp_f32_e32 v12, v116
	v_exp_f32_e32 v6, v102
	v_exp_f32_e32 v7, v103
	v_add_f32_e32 v116, v3, v2
	v_exp_f32_e32 v8, v104
	v_add_f32_e32 v116, v4, v116
	v_exp_f32_e32 v9, v105
	v_add_f32_e32 v116, v5, v116
	v_exp_f32_e32 v100, v106
	v_add_f32_e32 v116, v6, v116
	v_exp_f32_e32 v102, v107
	v_add_f32_e32 v116, v7, v116
	v_exp_f32_e32 v104, v108
	v_add_f32_e32 v116, v8, v116
	v_exp_f32_e32 v106, v109
	v_add_f32_e32 v116, v9, v116
	v_exp_f32_e32 v108, v110
	v_add_f32_e32 v116, v100, v116
	v_exp_f32_e32 v110, v111
	v_add_f32_e32 v116, v102, v116
	v_exp_f32_e32 v112, v112
	v_add_f32_e32 v116, v104, v116
	v_exp_f32_e32 v113, v113
	v_add_f32_e32 v116, v106, v116
	v_exp_f32_e32 v10, v114
	v_add_f32_e32 v116, v108, v116
	v_exp_f32_e32 v11, v115
	v_add_f32_e32 v116, v110, v116
	v_add_f32_e32 v116, v112, v116
	v_exp_f32_e32 v13, v117
	v_add_f32_e32 v116, v113, v116
	v_exp_f32_e32 v14, v118
	v_add_f32_e32 v116, v10, v116
	v_exp_f32_e32 v15, v119
	v_add_f32_e32 v116, v11, v116
	v_exp_f32_e32 v98, v120
	v_add_f32_e32 v116, v12, v116
	v_exp_f32_e32 v99, v121
	v_add_f32_e32 v116, v13, v116
	v_exp_f32_e32 v101, v122
	v_add_f32_e32 v116, v14, v116
	v_exp_f32_e32 v103, v123
	v_add_f32_e32 v116, v15, v116
	v_exp_f32_e32 v105, v124
	v_add_f32_e32 v116, v98, v116
	v_exp_f32_e32 v107, v125
	v_add_f32_e32 v116, v99, v116
	v_exp_f32_e32 v109, v126
	v_add_f32_e32 v116, v101, v116
	v_exp_f32_e32 v111, v127
	v_add_f32_e32 v116, v103, v116
	v_exp_f32_e32 v114, v128
	v_add_f32_e32 v116, v105, v116
	v_exp_f32_e32 v115, v129
	v_add_f32_e32 v116, v107, v116
	v_add_f32_e32 v116, v109, v116
	v_add_f32_e32 v116, v111, v116
	v_add_f32_e32 v116, v114, v116
	v_add_f32_e32 v116, v115, v116
	v_mov_b32_e32 v117, v116
	s_nop 1
	v_permlane32_swap_b32_e32 v116, v117
	v_add_f32_e32 v116, v116, v117
	v_fmac_f32_e32 v116, v80, v0
	v_cvt_pk_bf16_f32 v2, v2, v3
	v_cvt_pk_bf16_f32 v3, v4, v5
	v_cvt_pk_bf16_f32 v4, v6, v7
	v_cvt_pk_bf16_f32 v5, v8, v9
	v_cvt_pk_bf16_f32 v6, v100, v102
	v_cvt_pk_bf16_f32 v7, v104, v106
	v_cvt_pk_bf16_f32 v8, v108, v110
	v_cvt_pk_bf16_f32 v9, v112, v113
	v_cvt_pk_bf16_f32 v10, v10, v11
	v_cvt_pk_bf16_f32 v11, v12, v13
	v_cvt_pk_bf16_f32 v12, v14, v15
	v_cvt_pk_bf16_f32 v13, v98, v99
	v_cvt_pk_bf16_f32 v162, v101, v103
	v_cvt_pk_bf16_f32 v163, v105, v107
	v_cvt_pk_bf16_f32 v164, v109, v111
	v_cvt_pk_bf16_f32 v165, v114, v115
	s_nop 0
	v_permlane32_swap_b32_e32 v2, v4
	v_permlane32_swap_b32_e32 v3, v5
	v_permlane32_swap_b32_e32 v6, v8
	v_permlane32_swap_b32_e32 v7, v9
	v_permlane32_swap_b32_e32 v10, v12
	v_permlane32_swap_b32_e32 v11, v13
	v_permlane32_swap_b32_e32 v162, v164
	v_permlane32_swap_b32_e32 v163, v165
	v_mov_b32_e32 v80, v116
	s_branch .LBB0_371

.LBB0_371:
	v_cmp_gt_f32_e32 vcc, 1.0, v0
	s_cbranch_vccz .LBB0_375
	s_and_saveexec_b64 s[16:17], s[2:3]
	ds_write_b32 v190, v0 offset:128
	s_or_b64 exec, exec, s[16:17]
	s_waitcnt lgkmcnt(0)
	ds_read_b128 v[98:101], v189 offset:224
	ds_read_b128 v[102:105], v189 offset:192
	ds_read_b128 v[106:109], v189 offset:160
	ds_read_b128 v[110:113], v189 offset:128
	s_waitcnt lgkmcnt(3)
	v_pk_mul_f32 v[78:79], v[78:79], v[100:101]
	s_waitcnt lgkmcnt(2)
	v_pk_mul_f32 v[74:75], v[74:75], v[104:105]
	s_waitcnt lgkmcnt(1)
	v_pk_mul_f32 v[70:71], v[70:71], v[108:109]
	s_waitcnt lgkmcnt(0)
	v_pk_mul_f32 v[66:67], v[66:67], v[112:113]
	v_pk_mul_f32 v[76:77], v[76:77], v[98:99]
	v_pk_mul_f32 v[72:73], v[72:73], v[102:103]
	v_pk_mul_f32 v[68:69], v[68:69], v[106:107]
	v_pk_mul_f32 v[64:65], v[64:65], v[110:111]
	v_pk_mul_f32 v[62:63], v[62:63], v[100:101]
	v_pk_mul_f32 v[58:59], v[58:59], v[104:105]
	v_pk_mul_f32 v[54:55], v[54:55], v[108:109]
	v_pk_mul_f32 v[50:51], v[50:51], v[112:113]
	v_pk_mul_f32 v[60:61], v[60:61], v[98:99]
	v_pk_mul_f32 v[56:57], v[56:57], v[102:103]
	v_pk_mul_f32 v[52:53], v[52:53], v[106:107]
	v_pk_mul_f32 v[48:49], v[48:49], v[110:111]
	v_pk_mul_f32 v[46:47], v[46:47], v[100:101]
	v_pk_mul_f32 v[42:43], v[42:43], v[104:105]
	v_pk_mul_f32 v[38:39], v[38:39], v[108:109]
	v_pk_mul_f32 v[34:35], v[34:35], v[112:113]
	v_pk_mul_f32 v[44:45], v[44:45], v[98:99]
	v_pk_mul_f32 v[40:41], v[40:41], v[102:103]
	v_pk_mul_f32 v[36:37], v[36:37], v[106:107]
	v_pk_mul_f32 v[32:33], v[32:33], v[110:111]
	v_pk_mul_f32 v[30:31], v[30:31], v[100:101]
	v_pk_mul_f32 v[26:27], v[26:27], v[104:105]
	v_pk_mul_f32 v[22:23], v[22:23], v[108:109]
	v_pk_mul_f32 v[18:19], v[18:19], v[112:113]
	v_pk_mul_f32 v[28:29], v[28:29], v[98:99]
	v_pk_mul_f32 v[24:25], v[24:25], v[102:103]
	v_pk_mul_f32 v[20:21], v[20:21], v[106:107]
	v_pk_mul_f32 v[16:17], v[16:17], v[110:111]

; __device__ __forceinline__ bool softmax_pp(f32x16& p0, f32x16& p1, float& m_reg, float& l_reg, f32x16& negm, float& alpha, float& m_run, float dq, float nslope,
;                                            bf16x8& pa0, bf16x8& pa1, bf16x8& pa2, bf16x8& pa3) {
;     ...
;   float a = fmaxf(fmaxf(p0[0], p0[1]), p1[0]), bq = fmaxf(fmaxf(p0[2], p0[3]), p1[1]); a = fmaxf(fmaxf(a, p1[2]), p1[3]);
; #pragma unroll
;   for (int r = 4; r < 16; r += 4) { a = fmaxf(fmaxf(a, p0[r]), p0[r + 1]); bq = fmaxf(fmaxf(bq, p0[r + 2]), p0[r + 3]); a = fmaxf(fmaxf(a, p1[r]), p1[r + 1]); bq = fmaxf(fmaxf(bq, p1[r + 2]), p1[r + 3]); }
;   float pmax = fmaxf(a, bq);
;   { auto rr = __builtin_amdgcn_permlane32_swap(__float_as_uint(pmax), __float_as_uint(pmax), false, false);
;     pmax = fmaxf(__uint_as_float(rr[0]), __uint_as_float(rr[1])); }
;   alpha = 1.f;
;   { const float tmax = pmax + m_reg;
;     if (__all(tmax < m_run - TSKIP)) return false;
;     m_run = fmaxf(m_run, tmax); }
;   if (__builtin_expect(!__all(pmax <= THRL), 0)) { const float dl = fmaxf(pmax, 0.f); m_reg += dl; alpha = __builtin_amdgcn_exp2f(-dl);
; #pragma unroll
;     for (int r = 0; r < 16; ++r) { p0[r] -= dl; p1[r] -= dl; }
; #pragma unroll
;     for (int r = 0; r < 16; ++r) negm[r] = -m_reg; }
; #pragma unroll
;   for (int r = 0; r < 16; ++r) { p0[r] = __builtin_amdgcn_exp2f(p0[r]); p1[r] = __builtin_amdgcn_exp2f(p1[r]); }
;   float ps = 0;
; #pragma unroll
;   for (int r = 0; r < 16; ++r) ps += p0[r];
; #pragma unroll
;   for (int r = 0; r < 16; ++r) ps += p1[r];
;   { auto rr = __builtin_amdgcn_permlane32_swap(__float_as_uint(ps), __float_as_uint(ps), false, false);
;     ps = __uint_as_float(rr[0]) + __uint_as_float(rr[1]); }
;   l_reg = l_reg * alpha + ps;
;     ...
;   PK4(p0, 0, pa0); PK4(p0, 8, pa1); PK4(p1, 0, pa2); PK4(p1, 8, pa3);
.Lafter_bias_1:
	v_max_f32_e32 v0, v98, v99
	v_max3_f32 v14, v100, v101, v115
	v_max3_f32 v0, v0, v114, v116
	v_max3_f32 v0, v0, v117, v102
	v_max3_f32 v14, v14, v104, v105
	v_max3_f32 v0, v0, v103, v118
	v_max3_f32 v14, v14, v120, v121
	v_max3_f32 v0, v0, v119, v106
	v_max3_f32 v14, v14, v108, v109
	v_max3_f32 v0, v0, v107, v122
	v_max3_f32 v14, v14, v124, v125
	v_max3_f32 v0, v0, v123, v110
	v_max3_f32 v14, v14, v112, v113
	v_max3_f32 v0, v0, v111, v126
	v_max3_f32 v14, v14, v128, v129
	v_max3_f32 v0, v0, v127, v14
	v_mov_b32_e32 v14, v0
	s_nop 1
	v_permlane32_swap_b32_e32 v0, v14
	v_max_f32_e32 v167, v0, v14
	v_pk_add_f32 v[14:15], v[172:173], v[166:167]
	v_mov_b32_e32 v0, 1.0
	v_cmp_lt_f32_e32 vcc, v15, v14
	s_cmp_lg_u64 vcc, exec
	s_cselect_b64 s[14:15], -1, 0
	s_cmp_eq_u64 vcc, exec
	s_cbranch_scc1 .LBB0_385
	v_cmp_ge_f32_e32 vcc, s59, v167
	s_cmp_eq_u64 vcc, exec
	s_cbranch_scc0 .LBB0_396
	v_mov_b32_e32 v0, 1.0
.LBB0_384:
	v_max_f32_e32 v172, v172, v15
	v_exp_f32_e32 v2, v98
	v_exp_f32_e32 v3, v99
	v_exp_f32_e32 v4, v100
	v_exp_f32_e32 v5, v101
	v_exp_f32_e32 v12, v116
	v_exp_f32_e32 v6, v102
	v_exp_f32_e32 v7, v103
	v_add_f32_e32 v116, v3, v2
	v_exp_f32_e32 v8, v104
	v_add_f32_e32 v116, v4, v116
	v_exp_f32_e32 v9, v105
	v_add_f32_e32 v116, v5, v116
	v_exp_f32_e32 v100, v106
	v_add_f32_e32 v116, v6, v116
	v_exp_f32_e32 v102, v107
	v_add_f32_e32 v116, v7, v116
	v_exp_f32_e32 v104, v108
	v_add_f32_e32 v116, v8, v116
	v_exp_f32_e32 v106, v109
	v_add_f32_e32 v116, v9, v116
	v_exp_f32_e32 v108, v110
	v_add_f32_e32 v116, v100, v116
	v_exp_f32_e32 v110, v111
	v_add_f32_e32 v116, v102, v116
	v_exp_f32_e32 v112, v112
	v_add_f32_e32 v116, v104, v116
	v_exp_f32_e32 v113, v113
	v_add_f32_e32 v116, v106, v116
	v_exp_f32_e32 v10, v114
	v_add_f32_e32 v116, v108, v116
	v_exp_f32_e32 v11, v115
	v_add_f32_e32 v116, v110, v116
	v_add_f32_e32 v116, v112, v116
	v_exp_f32_e32 v13, v117
	v_add_f32_e32 v116, v113, v116
	v_exp_f32_e32 v14, v118
	v_add_f32_e32 v116, v10, v116
	v_exp_f32_e32 v15, v119
	v_add_f32_e32 v116, v11, v116
	v_exp_f32_e32 v98, v120
	v_add_f32_e32 v116, v12, v116
	v_exp_f32_e32 v99, v121
	v_add_f32_e32 v116, v13, v116
	v_exp_f32_e32 v101, v122
	v_add_f32_e32 v116, v14, v116
	v_exp_f32_e32 v103, v123
	v_add_f32_e32 v116, v15, v116
	v_exp_f32_e32 v105, v124
	v_add_f32_e32 v116, v98, v116
	v_exp_f32_e32 v107, v125
	v_add_f32_e32 v116, v99, v116
	v_exp_f32_e32 v109, v126
	v_add_f32_e32 v116, v101, v116
	v_exp_f32_e32 v111, v127
	v_add_f32_e32 v116, v103, v116
	v_exp_f32_e32 v114, v128
	v_add_f32_e32 v116, v105, v116
	v_exp_f32_e32 v115, v129
	v_add_f32_e32 v116, v107, v116
	v_add_f32_e32 v116, v109, v116
	v_add_f32_e32 v116, v111, v116
	v_add_f32_e32 v116, v114, v116
	v_add_f32_e32 v116, v115, v116
	v_mov_b32_e32 v117, v116
	s_nop 1
	v_permlane32_swap_b32_e32 v116, v117
	v_add_f32_e32 v116, v116, v117
	v_fmac_f32_e32 v116, v80, v0
	v_cvt_pk_bf16_f32 v2, v2, v3
	v_cvt_pk_bf16_f32 v3, v4, v5
	v_cvt_pk_bf16_f32 v4, v6, v7
	v_cvt_pk_bf16_f32 v5, v8, v9
	v_cvt_pk_bf16_f32 v6, v100, v102
	v_cvt_pk_bf16_f32 v7, v104, v106
	v_cvt_pk_bf16_f32 v8, v108, v110
	v_cvt_pk_bf16_f32 v9, v112, v113
	v_cvt_pk_bf16_f32 v10, v10, v11
	v_cvt_pk_bf16_f32 v11, v12, v13
	v_cvt_pk_bf16_f32 v12, v14, v15
	v_cvt_pk_bf16_f32 v13, v98, v99
	v_cvt_pk_bf16_f32 v162, v101, v103
	v_cvt_pk_bf16_f32 v163, v105, v107
	v_cvt_pk_bf16_f32 v164, v109, v111
	v_cvt_pk_bf16_f32 v165, v114, v115
	s_nop 0
	v_permlane32_swap_b32_e32 v2, v4
	v_permlane32_swap_b32_e32 v3, v5
	v_permlane32_swap_b32_e32 v6, v8
	v_permlane32_swap_b32_e32 v7, v9
	v_permlane32_swap_b32_e32 v10, v12
	v_permlane32_swap_b32_e32 v11, v13
	v_permlane32_swap_b32_e32 v162, v164
	v_permlane32_swap_b32_e32 v163, v165
	v_mov_b32_e32 v80, v116
